# P2 gates loop: the 64 lr LDS reads issued one token ahead into spare registers, counted lgkmcnt waits instead of lgkmcnt(0) after each read
# speedup vs baseline: 1.0048x; 1.0001x over previous
; #define LAS __attribute__((address_space(3)))
; __device__ __forceinline__ void gla_gates(const Params& p, int l, int h, int tok0, int d, int tg, LAS float* gsum, float (&b)[16], float& blast) {
;     LAS float* lrs = gsum + 25088;
;     {
;         const int t2 = threadIdx.x;
;         if (t2 < 256) *(LAS f32x4*)(lrs + t2 * 4) = *(const f32x4*)((const float*)(p.ws + WS_ZLR) + (size_t)tok0 * 16 + t2 * 4);
;     }
;     const float* wg = p.w_gate_up + (size_t)l * 16 * 512 + h * 128 + d;
;     float w[16];
; #pragma unroll
;     for (int r = 0; r < 16; ++r) w[r] = wg[r * 512];
;     const float bg = p.b_gate[l * 512 + h * 128 + d];
;     __syncthreads();
;     const LAS float* lr = lrs + (tg * 16) * 16;
;     float run = 0.f;
; #pragma unroll
;     for (int i = 0; i < 16; ++i) {
;         float x = bg;
; #pragma unroll
;         for (int r4 = 0; r4 < 4; ++r4) { const f32x4 a = *(const LAS f32x4*)(lr + i * 16 + r4 * 4);
;             x += a[0] * w[r4 * 4] + a[1] * w[r4 * 4 + 1] + a[2] * w[r4 * 4 + 2] + a[3] * w[r4 * 4 + 3]; }
;         const float ls = fminf(x, 0.f) - __logf(1.f + __expf(-fabsf(x)));
;         run += ls * (1.f / 16.f); b[i] = run;
;     }
.LBB0_505:
	s_or_b64 exec, exec, s[20:21]
	s_ashr_i32 s1, s0, 31
	s_lshl_b64 s[10:11], s[0:1], 15
	s_add_u32 s10, s76, s10
	v_lshlrev_b64 v[20:21], 9, v[18:19]
	s_addc_u32 s11, s25, s11
	v_lshlrev_b32_e32 v18, 2, v29
	v_mov_b32_e32 v19, v1
	v_lshl_add_u64 v[60:61], s[10:11], 0, v[18:19]
	v_add_co_u32_e32 v22, vcc, s4, v60
	global_load_dword v54, v18, s[10:11]
	global_load_dword v57, v18, s[10:11] offset:2048
	v_addc_co_u32_e32 v23, vcc, 0, v61, vcc
	v_add_co_u32_e32 v48, vcc, s92, v60
	s_movk_i32 s1, 0x4000
	s_nop 0
	v_addc_co_u32_e32 v49, vcc, 0, v61, vcc
	global_load_dword v58, v[48:49], off offset:-4096
	global_load_dword v59, v[22:23], off offset:2048
	global_load_dword v25, v[48:49], off
	s_nop 0
	global_load_dword v48, v[48:49], off offset:2048
	v_add_co_u32_e32 v22, vcc, s5, v60
	s_lshl_b32 s0, s0, 9
	s_nop 0
	v_addc_co_u32_e32 v23, vcc, 0, v61, vcc
	v_add_co_u32_e32 v52, vcc, s1, v60
	s_movk_i32 s1, 0x5000
	s_nop 0
	v_addc_co_u32_e32 v53, vcc, 0, v61, vcc
	global_load_dword v55, v[52:53], off offset:-4096
	global_load_dword v56, v[22:23], off offset:2048
	global_load_dword v50, v[52:53], off
	global_load_dword v51, v[52:53], off offset:2048
	v_add_co_u32_e32 v22, vcc, s1, v60
	s_movk_i32 s1, 0x6000
	s_nop 0
	v_addc_co_u32_e32 v23, vcc, 0, v61, vcc
	v_add_co_u32_e32 v62, vcc, s1, v60
	s_movk_i32 s1, 0x7000
	s_nop 0
	v_addc_co_u32_e32 v63, vcc, 0, v61, vcc
	v_add_co_u32_e32 v60, vcc, s1, v60
	s_or_b32 s0, s0, s28
	s_nop 0
	v_addc_co_u32_e32 v61, vcc, 0, v61, vcc
	global_load_dword v52, v[62:63], off offset:-4096
	global_load_dword v53, v[22:23], off offset:2048
	global_load_dword v19, v[62:63], off
	s_nop 0
	global_load_dword v22, v[62:63], off offset:2048
	global_load_dword v24, v[60:61], off
	global_load_dword v23, v[60:61], off offset:2048
	v_or_b32_e32 v60, s0, v29
	v_ashrrev_i32_e32 v61, 31, v60
	v_lshl_add_u64 v[60:61], v[60:61], 2, s[70:71]
	global_load_dword v61, v[60:61], off
	v_lshl_add_u32 v49, v31, 10, 0
	v_add_u32_e32 v60, 0x18800, v49
	s_waitcnt vmcnt(0)
	s_and_saveexec_b64 s[20:21], s[36:37]
	ds_write_b128 v201, v[66:69]
	s_or_b64 exec, exec, s[20:21]
	s_waitcnt vmcnt(0) lgkmcnt(0)
	s_barrier
	ds_read_b128 v[80:83], v60
	ds_read_b128 v[84:87], v60 offset:16
	ds_read_b128 v[88:91], v60 offset:32
	ds_read_b128 v[92:95], v60 offset:48
	ds_read_b128 v[96:99], v60 offset:64
	ds_read_b128 v[100:103], v60 offset:80
	ds_read_b128 v[104:107], v60 offset:96
	ds_read_b128 v[108:111], v60 offset:112
	v_lshl_add_u64 v[20:21], v[20:21], 1, s[78:79]
	s_waitcnt lgkmcnt(7)
	v_mul_f32_e32 v49, v57, v81
	v_fmac_f32_e32 v49, v54, v80
	v_fmac_f32_e32 v49, v58, v82
	v_fmac_f32_e32 v49, v59, v83
	s_waitcnt lgkmcnt(6)
	v_mul_f32_e32 v62, v48, v85
	v_fmac_f32_e32 v62, v25, v84
	v_fmac_f32_e32 v62, v55, v86
	v_fmac_f32_e32 v62, v56, v87
	v_add_f32_e32 v49, v61, v49
	v_add_f32_e32 v49, v49, v62
	s_waitcnt lgkmcnt(5)
	v_mul_f32_e32 v62, v51, v89
	v_fmac_f32_e32 v62, v50, v88
	v_fmac_f32_e32 v62, v52, v90
	v_fmac_f32_e32 v62, v53, v91
	v_add_f32_e32 v49, v49, v62
	s_waitcnt lgkmcnt(4)
	v_mul_f32_e32 v62, v22, v93
	v_fmac_f32_e32 v62, v19, v92
	v_fmac_f32_e32 v62, v24, v94
	v_fmac_f32_e32 v62, v23, v95
	v_add_f32_e32 v49, v49, v62
	v_min_f32_e32 v62, 0, v49
	v_mul_f32_e64 v49, |v49|, s8
	v_exp_f32_e32 v49, v49
	s_nop 0
	v_add_f32_e32 v49, 1.0, v49
	v_cmp_gt_f32_e32 vcc, s89, v49
	s_nop 1
	v_cndmask_b32_e64 v63, 0, 32, vcc
	v_ldexp_f32 v49, v49, v63
	v_log_f32_e32 v49, v49
	s_nop 0
	v_mul_f32_e32 v63, 0x3f317217, v49
	v_fma_f32 v63, v49, s9, -v63
	v_fmac_f32_e32 v63, 0x3377d1cf, v49
	v_fmac_f32_e32 v63, 0x3f317217, v49
	v_cmp_lt_f32_e64 s[0:1], |v49|, s88
	s_nop 1
	v_cndmask_b32_e64 v49, v49, v63, s[0:1]
	v_cndmask_b32_e32 v63, 0, v206, vcc
	v_sub_f32_e32 v49, v49, v63
	v_sub_f32_e32 v49, v62, v49
	ds_read_b128 v[80:83], v60 offset:128
	s_mov_b32 s0, 0x3d800000
	v_fma_f32 v49, v49, s0, 0
	s_waitcnt lgkmcnt(4)
	v_mul_f32_e32 v63, v57, v97
	v_fmac_f32_e32 v63, v54, v96
	v_fmac_f32_e32 v63, v58, v98
	v_fmac_f32_e32 v63, v59, v99
	v_add_f32_e32 v66, v61, v63
	ds_read_b128 v[84:87], v60 offset:144
	s_waitcnt lgkmcnt(4)
	v_mul_f32_e32 v63, v48, v101
	v_fmac_f32_e32 v63, v25, v100
	v_fmac_f32_e32 v63, v55, v102
	v_fmac_f32_e32 v63, v56, v103
	v_add_f32_e32 v66, v66, v63
	ds_read_b128 v[88:91], v60 offset:160
	s_waitcnt lgkmcnt(4)
	v_mul_f32_e32 v63, v51, v105
	v_fmac_f32_e32 v63, v50, v104
	v_fmac_f32_e32 v63, v52, v106
	v_fmac_f32_e32 v63, v53, v107
	v_add_f32_e32 v66, v66, v63
	ds_read_b128 v[92:95], v60 offset:176
	s_waitcnt lgkmcnt(4)
	v_mul_f32_e32 v63, v22, v109
	v_fmac_f32_e32 v63, v19, v108
	v_fmac_f32_e32 v63, v24, v110
	v_fmac_f32_e32 v63, v23, v111
	v_add_f32_e32 v62, v66, v63
	v_min_f32_e32 v63, 0, v62
	v_mul_f32_e64 v62, |v62|, s8
	v_exp_f32_e32 v62, v62
	s_nop 0
	v_add_f32_e32 v62, 1.0, v62
	v_cmp_gt_f32_e32 vcc, s89, v62
	s_nop 1
	v_cndmask_b32_e64 v64, 0, 32, vcc
	v_ldexp_f32 v62, v62, v64
	v_log_f32_e32 v62, v62
	s_nop 0
	v_mul_f32_e32 v64, 0x3f317217, v62
	v_fma_f32 v64, v62, s9, -v64
	v_fmac_f32_e32 v64, 0x3377d1cf, v62
	v_fmac_f32_e32 v64, 0x3f317217, v62
	v_cmp_lt_f32_e64 s[0:1], |v62|, s88
	s_nop 1
	v_cndmask_b32_e64 v62, v62, v64, s[0:1]
	v_cndmask_b32_e32 v64, 0, v206, vcc
	v_sub_f32_e32 v62, v62, v64
	ds_read_b128 v[96:99], v60 offset:192
	v_sub_f32_e32 v62, v63, v62
	v_fmamk_f32 v62, v62, 0x3d800000, v49
	s_waitcnt lgkmcnt(4)
	v_mul_f32_e32 v63, v57, v81
	v_fmac_f32_e32 v63, v54, v80
	v_fmac_f32_e32 v63, v58, v82
	v_fmac_f32_e32 v63, v59, v83
	ds_read_b128 v[100:103], v60 offset:208
	v_add_f32_e32 v63, v61, v63
	s_waitcnt lgkmcnt(4)
; #define LAS __attribute__((address_space(3)))
; __device__ __forceinline__ void gla_gates(const Params& p, int l, int h, int tok0, int d, int tg, LAS float* gsum, float (&b)[16], float& blast) {
;     ...
;     const LAS float* lr = lrs + (tg * 16) * 16;
;     float run = 0.f;
; #pragma unroll
;     for (int i = 0; i < 16; ++i) {
;         float x = bg;
; #pragma unroll
;         for (int r4 = 0; r4 < 4; ++r4) { const f32x4 a = *(const LAS f32x4*)(lr + i * 16 + r4 * 4);
;             x += a[0] * w[r4 * 4] + a[1] * w[r4 * 4 + 1] + a[2] * w[r4 * 4 + 2] + a[3] * w[r4 * 4 + 3]; }
;         const float ls = fminf(x, 0.f) - __logf(1.f + __expf(-fabsf(x)));
;         run += ls * (1.f / 16.f); b[i] = run;
;     }
	v_mul_f32_e32 v65, v48, v85
	v_fmac_f32_e32 v65, v25, v84
	v_fmac_f32_e32 v65, v55, v86
	v_fmac_f32_e32 v65, v56, v87
	v_add_f32_e32 v63, v63, v65
	ds_read_b128 v[104:107], v60 offset:224
	s_waitcnt lgkmcnt(4)
	v_mul_f32_e32 v65, v51, v89
	v_fmac_f32_e32 v65, v50, v88
	v_fmac_f32_e32 v65, v52, v90
	v_fmac_f32_e32 v65, v53, v91
	v_add_f32_e32 v63, v63, v65
	ds_read_b128 v[108:111], v60 offset:240
	s_waitcnt lgkmcnt(4)
	v_mul_f32_e32 v65, v22, v93
	v_fmac_f32_e32 v65, v19, v92
	v_fmac_f32_e32 v65, v24, v94
	v_fmac_f32_e32 v65, v23, v95
	v_add_f32_e32 v63, v63, v65
	v_min_f32_e32 v64, 0, v63
	v_mul_f32_e64 v63, |v63|, s8
	v_exp_f32_e32 v63, v63
	s_nop 0
	v_add_f32_e32 v63, 1.0, v63
	v_cmp_gt_f32_e32 vcc, s89, v63
	s_nop 1
	v_cndmask_b32_e64 v65, 0, 32, vcc
	v_ldexp_f32 v63, v63, v65
	v_log_f32_e32 v63, v63
	s_nop 0
	v_mul_f32_e32 v65, 0x3f317217, v63
	v_fma_f32 v65, v63, s9, -v65
	v_fmac_f32_e32 v65, 0x3377d1cf, v63
	v_fmac_f32_e32 v65, 0x3f317217, v63
	v_cmp_lt_f32_e64 s[0:1], |v63|, s88
	s_nop 1
	v_cndmask_b32_e64 v63, v63, v65, s[0:1]
	v_cndmask_b32_e32 v65, 0, v206, vcc
	v_sub_f32_e32 v63, v63, v65
	v_sub_f32_e32 v63, v64, v63
	ds_read_b128 v[80:83], v60 offset:256
	v_fmamk_f32 v63, v63, 0x3d800000, v62
	s_waitcnt lgkmcnt(4)
	v_mul_f32_e32 v65, v57, v97
	v_fmac_f32_e32 v65, v54, v96
	v_fmac_f32_e32 v65, v58, v98
	v_fmac_f32_e32 v65, v59, v99
	v_add_f32_e32 v68, v61, v65
	ds_read_b128 v[84:87], v60 offset:272
	s_waitcnt lgkmcnt(4)
	v_mul_f32_e32 v65, v48, v101
	v_fmac_f32_e32 v65, v25, v100
	v_fmac_f32_e32 v65, v55, v102
	v_fmac_f32_e32 v65, v56, v103
	v_add_f32_e32 v68, v68, v65
	ds_read_b128 v[88:91], v60 offset:288
	s_waitcnt lgkmcnt(4)
	v_mul_f32_e32 v65, v51, v105
	v_fmac_f32_e32 v65, v50, v104
	v_fmac_f32_e32 v65, v52, v106
	v_fmac_f32_e32 v65, v53, v107
	v_add_f32_e32 v68, v68, v65
	ds_read_b128 v[92:95], v60 offset:304
	s_waitcnt lgkmcnt(4)
	v_mul_f32_e32 v65, v22, v109
	v_fmac_f32_e32 v65, v19, v108
	v_fmac_f32_e32 v65, v24, v110
	v_fmac_f32_e32 v65, v23, v111
	v_add_f32_e32 v64, v68, v65
	v_min_f32_e32 v65, 0, v64
	v_mul_f32_e64 v64, |v64|, s8
	v_exp_f32_e32 v64, v64
	s_nop 0
	v_add_f32_e32 v64, 1.0, v64
	v_cmp_gt_f32_e32 vcc, s89, v64
	s_nop 1
	v_cndmask_b32_e64 v66, 0, 32, vcc
	v_ldexp_f32 v64, v64, v66
	v_log_f32_e32 v64, v64
	s_nop 0
	v_mul_f32_e32 v66, 0x3f317217, v64
	v_fma_f32 v66, v64, s9, -v66
	v_fmac_f32_e32 v66, 0x3377d1cf, v64
	v_fmac_f32_e32 v66, 0x3f317217, v64
	v_cmp_lt_f32_e64 s[0:1], |v64|, s88
	s_nop 1
	v_cndmask_b32_e64 v64, v64, v66, s[0:1]
	v_cndmask_b32_e32 v66, 0, v206, vcc
	v_sub_f32_e32 v64, v64, v66
	ds_read_b128 v[96:99], v60 offset:320
	v_sub_f32_e32 v64, v65, v64
	v_fmamk_f32 v64, v64, 0x3d800000, v63
	s_waitcnt lgkmcnt(4)
	v_mul_f32_e32 v65, v57, v81
	v_fmac_f32_e32 v65, v54, v80
	v_fmac_f32_e32 v65, v58, v82
	v_fmac_f32_e32 v65, v59, v83
	ds_read_b128 v[100:103], v60 offset:336
	v_add_f32_e32 v65, v61, v65
	s_waitcnt lgkmcnt(4)
	v_mul_f32_e32 v67, v48, v85
	v_fmac_f32_e32 v67, v25, v84
	v_fmac_f32_e32 v67, v55, v86
	v_fmac_f32_e32 v67, v56, v87
	v_add_f32_e32 v65, v65, v67
	ds_read_b128 v[104:107], v60 offset:352
	s_waitcnt lgkmcnt(4)
	v_mul_f32_e32 v67, v51, v89
	v_fmac_f32_e32 v67, v50, v88
	v_fmac_f32_e32 v67, v52, v90
	v_fmac_f32_e32 v67, v53, v91
	v_add_f32_e32 v65, v65, v67
	ds_read_b128 v[108:111], v60 offset:368
	s_waitcnt lgkmcnt(4)
	v_mul_f32_e32 v67, v22, v93
	v_fmac_f32_e32 v67, v19, v92
	v_fmac_f32_e32 v67, v24, v94
	v_fmac_f32_e32 v67, v23, v95
	v_add_f32_e32 v65, v65, v67
	v_min_f32_e32 v66, 0, v65
	v_mul_f32_e64 v65, |v65|, s8
	v_exp_f32_e32 v65, v65
	s_nop 0
	v_add_f32_e32 v65, 1.0, v65
	v_cmp_gt_f32_e32 vcc, s89, v65
	s_nop 1
	v_cndmask_b32_e64 v67, 0, 32, vcc
	v_ldexp_f32 v65, v65, v67
	v_log_f32_e32 v65, v65
	s_nop 0
	v_mul_f32_e32 v67, 0x3f317217, v65
	v_fma_f32 v67, v65, s9, -v67
	v_fmac_f32_e32 v67, 0x3377d1cf, v65
	v_fmac_f32_e32 v67, 0x3f317217, v65
	v_cmp_lt_f32_e64 s[0:1], |v65|, s88
	s_nop 1
	v_cndmask_b32_e64 v65, v65, v67, s[0:1]
	v_cndmask_b32_e32 v67, 0, v206, vcc
	v_sub_f32_e32 v65, v65, v67
	v_sub_f32_e32 v65, v66, v65
	ds_read_b128 v[80:83], v60 offset:384
	v_fmamk_f32 v65, v65, 0x3d800000, v64
	s_waitcnt lgkmcnt(4)
	v_mul_f32_e32 v67, v57, v97
	v_fmac_f32_e32 v67, v54, v96
	v_fmac_f32_e32 v67, v58, v98
	v_fmac_f32_e32 v67, v59, v99
	v_add_f32_e32 v70, v61, v67
	ds_read_b128 v[84:87], v60 offset:400
	s_waitcnt lgkmcnt(4)
	v_mul_f32_e32 v67, v48, v101
	v_fmac_f32_e32 v67, v25, v100
	v_fmac_f32_e32 v67, v55, v102
	v_fmac_f32_e32 v67, v56, v103
	v_add_f32_e32 v70, v70, v67
	ds_read_b128 v[88:91], v60 offset:416
	s_waitcnt lgkmcnt(4)
	v_mul_f32_e32 v67, v51, v105
	v_fmac_f32_e32 v67, v50, v104
	v_fmac_f32_e32 v67, v52, v106
	v_fmac_f32_e32 v67, v53, v107
	v_add_f32_e32 v70, v70, v67
	ds_read_b128 v[92:95], v60 offset:432
	s_waitcnt lgkmcnt(4)
	v_mul_f32_e32 v67, v22, v109
	v_fmac_f32_e32 v67, v19, v108
	v_fmac_f32_e32 v67, v24, v110
	v_fmac_f32_e32 v67, v23, v111
	v_add_f32_e32 v66, v70, v67
	v_min_f32_e32 v67, 0, v66
	v_mul_f32_e64 v66, |v66|, s8
	v_exp_f32_e32 v66, v66
	s_nop 0
	v_add_f32_e32 v66, 1.0, v66
	v_cmp_gt_f32_e32 vcc, s89, v66
	s_nop 1
	v_cndmask_b32_e64 v68, 0, 32, vcc
	v_ldexp_f32 v66, v66, v68
	v_log_f32_e32 v66, v66
	s_nop 0
	v_mul_f32_e32 v68, 0x3f317217, v66
	v_fma_f32 v68, v66, s9, -v68
	v_fmac_f32_e32 v68, 0x3377d1cf, v66
	v_fmac_f32_e32 v68, 0x3f317217, v66
	v_cmp_lt_f32_e64 s[0:1], |v66|, s88
	s_nop 1
	v_cndmask_b32_e64 v66, v66, v68, s[0:1]
	v_cndmask_b32_e32 v68, 0, v206, vcc
	v_sub_f32_e32 v66, v66, v68
	ds_read_b128 v[96:99], v60 offset:448
	v_sub_f32_e32 v66, v67, v66
	v_fmamk_f32 v66, v66, 0x3d800000, v65
	s_waitcnt lgkmcnt(4)
; #define LAS __attribute__((address_space(3)))
; __device__ __forceinline__ void gla_gates(const Params& p, int l, int h, int tok0, int d, int tg, LAS float* gsum, float (&b)[16], float& blast) {
;     ...
;     const LAS float* lr = lrs + (tg * 16) * 16;
;     float run = 0.f;
; #pragma unroll
;     for (int i = 0; i < 16; ++i) {
;         float x = bg;
; #pragma unroll
;         for (int r4 = 0; r4 < 4; ++r4) { const f32x4 a = *(const LAS f32x4*)(lr + i * 16 + r4 * 4);
;             x += a[0] * w[r4 * 4] + a[1] * w[r4 * 4 + 1] + a[2] * w[r4 * 4 + 2] + a[3] * w[r4 * 4 + 3]; }
;         const float ls = fminf(x, 0.f) - __logf(1.f + __expf(-fabsf(x)));
;         run += ls * (1.f / 16.f); b[i] = run;
;     }
	v_mul_f32_e32 v67, v57, v81
	v_fmac_f32_e32 v67, v54, v80
	v_fmac_f32_e32 v67, v58, v82
	v_fmac_f32_e32 v67, v59, v83
	ds_read_b128 v[100:103], v60 offset:464
	v_add_f32_e32 v67, v61, v67
	s_waitcnt lgkmcnt(4)
	v_mul_f32_e32 v69, v48, v85
	v_fmac_f32_e32 v69, v25, v84
	v_fmac_f32_e32 v69, v55, v86
	v_fmac_f32_e32 v69, v56, v87
	v_add_f32_e32 v67, v67, v69
	ds_read_b128 v[104:107], v60 offset:480
	s_waitcnt lgkmcnt(4)
	v_mul_f32_e32 v69, v51, v89
	v_fmac_f32_e32 v69, v50, v88
	v_fmac_f32_e32 v69, v52, v90
	v_fmac_f32_e32 v69, v53, v91
	v_add_f32_e32 v67, v67, v69
	ds_read_b128 v[108:111], v60 offset:496
	s_waitcnt lgkmcnt(4)
	v_mul_f32_e32 v69, v22, v93
	v_fmac_f32_e32 v69, v19, v92
	v_fmac_f32_e32 v69, v24, v94
	v_fmac_f32_e32 v69, v23, v95
	v_add_f32_e32 v67, v67, v69
	v_min_f32_e32 v68, 0, v67
	v_mul_f32_e64 v67, |v67|, s8
	v_exp_f32_e32 v67, v67
	s_nop 0
	v_add_f32_e32 v67, 1.0, v67
	v_cmp_gt_f32_e32 vcc, s89, v67
	s_nop 1
	v_cndmask_b32_e64 v69, 0, 32, vcc
	v_ldexp_f32 v67, v67, v69
	v_log_f32_e32 v67, v67
	s_nop 0
	v_mul_f32_e32 v69, 0x3f317217, v67
	v_fma_f32 v69, v67, s9, -v69
	v_fmac_f32_e32 v69, 0x3377d1cf, v67
	v_fmac_f32_e32 v69, 0x3f317217, v67
	v_cmp_lt_f32_e64 s[0:1], |v67|, s88
	s_nop 1
	v_cndmask_b32_e64 v67, v67, v69, s[0:1]
	v_cndmask_b32_e32 v69, 0, v206, vcc
	v_sub_f32_e32 v67, v67, v69
	v_sub_f32_e32 v67, v68, v67
	ds_read_b128 v[80:83], v60 offset:512
	v_fmamk_f32 v67, v67, 0x3d800000, v66
	s_waitcnt lgkmcnt(4)
	v_mul_f32_e32 v69, v57, v97
	v_fmac_f32_e32 v69, v54, v96
	v_fmac_f32_e32 v69, v58, v98
	v_fmac_f32_e32 v69, v59, v99
	v_add_f32_e32 v72, v61, v69
	ds_read_b128 v[84:87], v60 offset:528
	s_waitcnt lgkmcnt(4)
	v_mul_f32_e32 v69, v48, v101
	v_fmac_f32_e32 v69, v25, v100
	v_fmac_f32_e32 v69, v55, v102
	v_fmac_f32_e32 v69, v56, v103
	v_add_f32_e32 v72, v72, v69
	ds_read_b128 v[88:91], v60 offset:544
	s_waitcnt lgkmcnt(4)
	v_mul_f32_e32 v69, v51, v105
	v_fmac_f32_e32 v69, v50, v104
	v_fmac_f32_e32 v69, v52, v106
	v_fmac_f32_e32 v69, v53, v107
	v_add_f32_e32 v72, v72, v69
	ds_read_b128 v[92:95], v60 offset:560
	s_waitcnt lgkmcnt(4)
	v_mul_f32_e32 v69, v22, v109
	v_fmac_f32_e32 v69, v19, v108
	v_fmac_f32_e32 v69, v24, v110
	v_fmac_f32_e32 v69, v23, v111
	v_add_f32_e32 v68, v72, v69
	v_min_f32_e32 v69, 0, v68
	v_mul_f32_e64 v68, |v68|, s8
	v_exp_f32_e32 v68, v68
	s_nop 0
	v_add_f32_e32 v68, 1.0, v68
	v_cmp_gt_f32_e32 vcc, s89, v68
	s_nop 1
	v_cndmask_b32_e64 v70, 0, 32, vcc
	v_ldexp_f32 v68, v68, v70
	v_log_f32_e32 v68, v68
	s_nop 0
	v_mul_f32_e32 v70, 0x3f317217, v68
	v_fma_f32 v70, v68, s9, -v70
	v_fmac_f32_e32 v70, 0x3377d1cf, v68
	v_fmac_f32_e32 v70, 0x3f317217, v68
	v_cmp_lt_f32_e64 s[0:1], |v68|, s88
	s_nop 1
	v_cndmask_b32_e64 v68, v68, v70, s[0:1]
	v_cndmask_b32_e32 v70, 0, v206, vcc
	v_sub_f32_e32 v68, v68, v70
	ds_read_b128 v[96:99], v60 offset:576
	v_sub_f32_e32 v68, v69, v68
	v_fmamk_f32 v68, v68, 0x3d800000, v67
	s_waitcnt lgkmcnt(4)
	v_mul_f32_e32 v69, v57, v81
	v_fmac_f32_e32 v69, v54, v80
	v_fmac_f32_e32 v69, v58, v82
	v_fmac_f32_e32 v69, v59, v83
	ds_read_b128 v[100:103], v60 offset:592
	v_add_f32_e32 v69, v61, v69
	s_waitcnt lgkmcnt(4)
	v_mul_f32_e32 v71, v48, v85
	v_fmac_f32_e32 v71, v25, v84
	v_fmac_f32_e32 v71, v55, v86
	v_fmac_f32_e32 v71, v56, v87
	v_add_f32_e32 v69, v69, v71
	ds_read_b128 v[104:107], v60 offset:608
	s_waitcnt lgkmcnt(4)
	v_mul_f32_e32 v71, v51, v89
	v_fmac_f32_e32 v71, v50, v88
	v_fmac_f32_e32 v71, v52, v90
	v_fmac_f32_e32 v71, v53, v91
	v_add_f32_e32 v69, v69, v71
	ds_read_b128 v[108:111], v60 offset:624
	s_waitcnt lgkmcnt(4)
	v_mul_f32_e32 v71, v22, v93
	v_fmac_f32_e32 v71, v19, v92
	v_fmac_f32_e32 v71, v24, v94
	v_fmac_f32_e32 v71, v23, v95
	v_add_f32_e32 v69, v69, v71
	v_min_f32_e32 v70, 0, v69
	v_mul_f32_e64 v69, |v69|, s8
	v_exp_f32_e32 v69, v69
	s_nop 0
	v_add_f32_e32 v69, 1.0, v69
	v_cmp_gt_f32_e32 vcc, s89, v69
	s_nop 1
	v_cndmask_b32_e64 v71, 0, 32, vcc
	v_ldexp_f32 v69, v69, v71
	v_log_f32_e32 v69, v69
	s_nop 0
	v_mul_f32_e32 v71, 0x3f317217, v69
	v_fma_f32 v71, v69, s9, -v71
	v_fmac_f32_e32 v71, 0x3377d1cf, v69
	v_fmac_f32_e32 v71, 0x3f317217, v69
	v_cmp_lt_f32_e64 s[0:1], |v69|, s88
	s_nop 1
	v_cndmask_b32_e64 v69, v69, v71, s[0:1]
	v_cndmask_b32_e32 v71, 0, v206, vcc
	v_sub_f32_e32 v69, v69, v71
	v_sub_f32_e32 v69, v70, v69
	ds_read_b128 v[80:83], v60 offset:640
	v_fmamk_f32 v69, v69, 0x3d800000, v68
	s_waitcnt lgkmcnt(4)
	v_mul_f32_e32 v71, v57, v97
	v_fmac_f32_e32 v71, v54, v96
	v_fmac_f32_e32 v71, v58, v98
	v_fmac_f32_e32 v71, v59, v99
	v_add_f32_e32 v74, v61, v71
	ds_read_b128 v[84:87], v60 offset:656
	s_waitcnt lgkmcnt(4)
	v_mul_f32_e32 v71, v48, v101
	v_fmac_f32_e32 v71, v25, v100
	v_fmac_f32_e32 v71, v55, v102
	v_fmac_f32_e32 v71, v56, v103
	v_add_f32_e32 v74, v74, v71
	ds_read_b128 v[88:91], v60 offset:672
	s_waitcnt lgkmcnt(4)
	v_mul_f32_e32 v71, v51, v105
	v_fmac_f32_e32 v71, v50, v104
	v_fmac_f32_e32 v71, v52, v106
	v_fmac_f32_e32 v71, v53, v107
	v_add_f32_e32 v74, v74, v71
	ds_read_b128 v[92:95], v60 offset:688
	s_waitcnt lgkmcnt(4)
	v_mul_f32_e32 v71, v22, v109
	v_fmac_f32_e32 v71, v19, v108
	v_fmac_f32_e32 v71, v24, v110
	v_fmac_f32_e32 v71, v23, v111
	v_add_f32_e32 v70, v74, v71
	v_min_f32_e32 v71, 0, v70
	v_mul_f32_e64 v70, |v70|, s8
	v_exp_f32_e32 v70, v70
	s_nop 0
	v_add_f32_e32 v70, 1.0, v70
	v_cmp_gt_f32_e32 vcc, s89, v70
	s_nop 1
	v_cndmask_b32_e64 v72, 0, 32, vcc
	v_ldexp_f32 v70, v70, v72
	v_log_f32_e32 v70, v70
	s_nop 0
	v_mul_f32_e32 v72, 0x3f317217, v70
	v_fma_f32 v72, v70, s9, -v72
	v_fmac_f32_e32 v72, 0x3377d1cf, v70
	v_fmac_f32_e32 v72, 0x3f317217, v70
	v_cmp_lt_f32_e64 s[0:1], |v70|, s88
	s_nop 1
	v_cndmask_b32_e64 v70, v70, v72, s[0:1]
	v_cndmask_b32_e32 v72, 0, v206, vcc
	v_sub_f32_e32 v70, v70, v72
	ds_read_b128 v[96:99], v60 offset:704
	v_sub_f32_e32 v70, v71, v70
	v_fmamk_f32 v70, v70, 0x3d800000, v69
	s_waitcnt lgkmcnt(4)
; #define LAS __attribute__((address_space(3)))
; __device__ __forceinline__ void gla_gates(const Params& p, int l, int h, int tok0, int d, int tg, LAS float* gsum, float (&b)[16], float& blast) {
;     ...
;     const LAS float* lr = lrs + (tg * 16) * 16;
;     float run = 0.f;
; #pragma unroll
;     for (int i = 0; i < 16; ++i) {
;         float x = bg;
; #pragma unroll
;         for (int r4 = 0; r4 < 4; ++r4) { const f32x4 a = *(const LAS f32x4*)(lr + i * 16 + r4 * 4);
;             x += a[0] * w[r4 * 4] + a[1] * w[r4 * 4 + 1] + a[2] * w[r4 * 4 + 2] + a[3] * w[r4 * 4 + 3]; }
;         const float ls = fminf(x, 0.f) - __logf(1.f + __expf(-fabsf(x)));
;         run += ls * (1.f / 16.f); b[i] = run;
;     }
	v_mul_f32_e32 v71, v57, v81
	v_fmac_f32_e32 v71, v54, v80
	v_fmac_f32_e32 v71, v58, v82
	v_fmac_f32_e32 v71, v59, v83
	ds_read_b128 v[100:103], v60 offset:720
	v_add_f32_e32 v71, v61, v71
	s_waitcnt lgkmcnt(4)
	v_mul_f32_e32 v73, v48, v85
	v_fmac_f32_e32 v73, v25, v84
	v_fmac_f32_e32 v73, v55, v86
	v_fmac_f32_e32 v73, v56, v87
	v_add_f32_e32 v71, v71, v73
	ds_read_b128 v[104:107], v60 offset:736
	s_waitcnt lgkmcnt(4)
	v_mul_f32_e32 v73, v51, v89
	v_fmac_f32_e32 v73, v50, v88
	v_fmac_f32_e32 v73, v52, v90
	v_fmac_f32_e32 v73, v53, v91
	v_add_f32_e32 v71, v71, v73
	ds_read_b128 v[108:111], v60 offset:752
	s_waitcnt lgkmcnt(4)
	v_mul_f32_e32 v73, v22, v93
	v_fmac_f32_e32 v73, v19, v92
	v_fmac_f32_e32 v73, v24, v94
	v_fmac_f32_e32 v73, v23, v95
	v_add_f32_e32 v71, v71, v73
	v_min_f32_e32 v72, 0, v71
	v_mul_f32_e64 v71, |v71|, s8
	v_exp_f32_e32 v71, v71
	s_nop 0
	v_add_f32_e32 v71, 1.0, v71
	v_cmp_gt_f32_e32 vcc, s89, v71
	s_nop 1
	v_cndmask_b32_e64 v73, 0, 32, vcc
	v_ldexp_f32 v71, v71, v73
	v_log_f32_e32 v71, v71
	s_nop 0
	v_mul_f32_e32 v73, 0x3f317217, v71
	v_fma_f32 v73, v71, s9, -v73
	v_fmac_f32_e32 v73, 0x3377d1cf, v71
	v_fmac_f32_e32 v73, 0x3f317217, v71
	v_cmp_lt_f32_e64 s[0:1], |v71|, s88
	s_nop 1
	v_cndmask_b32_e64 v71, v71, v73, s[0:1]
	v_cndmask_b32_e32 v73, 0, v206, vcc
	v_sub_f32_e32 v71, v71, v73
	v_sub_f32_e32 v71, v72, v71
	ds_read_b128 v[80:83], v60 offset:768
	v_fmamk_f32 v71, v71, 0x3d800000, v70
	s_waitcnt lgkmcnt(4)
	v_mul_f32_e32 v73, v57, v97
	v_fmac_f32_e32 v73, v54, v96
	v_fmac_f32_e32 v73, v58, v98
	v_fmac_f32_e32 v73, v59, v99
	v_add_f32_e32 v76, v61, v73
	ds_read_b128 v[84:87], v60 offset:784
	s_waitcnt lgkmcnt(4)
	v_mul_f32_e32 v73, v48, v101
	v_fmac_f32_e32 v73, v25, v100
	v_fmac_f32_e32 v73, v55, v102
	v_fmac_f32_e32 v73, v56, v103
	v_add_f32_e32 v76, v76, v73
	ds_read_b128 v[88:91], v60 offset:800
	s_waitcnt lgkmcnt(4)
	v_mul_f32_e32 v73, v51, v105
	v_fmac_f32_e32 v73, v50, v104
	v_fmac_f32_e32 v73, v52, v106
	v_fmac_f32_e32 v73, v53, v107
	v_add_f32_e32 v76, v76, v73
	ds_read_b128 v[92:95], v60 offset:816
	s_waitcnt lgkmcnt(4)
	v_mul_f32_e32 v73, v22, v109
	v_fmac_f32_e32 v73, v19, v108
	v_fmac_f32_e32 v73, v24, v110
	v_fmac_f32_e32 v73, v23, v111
	v_add_f32_e32 v72, v76, v73
	v_min_f32_e32 v73, 0, v72
	v_mul_f32_e64 v72, |v72|, s8
	v_exp_f32_e32 v72, v72
	s_nop 0
	v_add_f32_e32 v72, 1.0, v72
	v_cmp_gt_f32_e32 vcc, s89, v72
	s_nop 1
	v_cndmask_b32_e64 v74, 0, 32, vcc
	v_ldexp_f32 v72, v72, v74
	v_log_f32_e32 v72, v72
	s_nop 0
	v_mul_f32_e32 v74, 0x3f317217, v72
	v_fma_f32 v74, v72, s9, -v74
	v_fmac_f32_e32 v74, 0x3377d1cf, v72
	v_fmac_f32_e32 v74, 0x3f317217, v72
	v_cmp_lt_f32_e64 s[0:1], |v72|, s88
	s_nop 1
	v_cndmask_b32_e64 v72, v72, v74, s[0:1]
	v_cndmask_b32_e32 v74, 0, v206, vcc
	v_sub_f32_e32 v72, v72, v74
	ds_read_b128 v[96:99], v60 offset:832
	v_sub_f32_e32 v72, v73, v72
	v_fmamk_f32 v72, v72, 0x3d800000, v71
	s_waitcnt lgkmcnt(4)
	v_mul_f32_e32 v73, v57, v81
	v_fmac_f32_e32 v73, v54, v80
	v_fmac_f32_e32 v73, v58, v82
	v_fmac_f32_e32 v73, v59, v83
	ds_read_b128 v[100:103], v60 offset:848
	v_add_f32_e32 v73, v61, v73
	s_waitcnt lgkmcnt(4)
	v_mul_f32_e32 v75, v48, v85
	v_fmac_f32_e32 v75, v25, v84
	v_fmac_f32_e32 v75, v55, v86
	v_fmac_f32_e32 v75, v56, v87
	v_add_f32_e32 v73, v73, v75
	ds_read_b128 v[104:107], v60 offset:864
	s_waitcnt lgkmcnt(4)
	v_mul_f32_e32 v75, v51, v89
	v_fmac_f32_e32 v75, v50, v88
	v_fmac_f32_e32 v75, v52, v90
	v_fmac_f32_e32 v75, v53, v91
	v_add_f32_e32 v73, v73, v75
	ds_read_b128 v[108:111], v60 offset:880
	s_waitcnt lgkmcnt(4)
	v_mul_f32_e32 v75, v22, v93
	v_fmac_f32_e32 v75, v19, v92
	v_fmac_f32_e32 v75, v24, v94
	v_fmac_f32_e32 v75, v23, v95
	v_add_f32_e32 v73, v73, v75
	v_min_f32_e32 v74, 0, v73
	v_mul_f32_e64 v73, |v73|, s8
	v_exp_f32_e32 v73, v73
	s_nop 0
	v_add_f32_e32 v73, 1.0, v73
	v_cmp_gt_f32_e32 vcc, s89, v73
	s_nop 1
	v_cndmask_b32_e64 v75, 0, 32, vcc
	v_ldexp_f32 v73, v73, v75
	v_log_f32_e32 v73, v73
	s_nop 0
	v_mul_f32_e32 v75, 0x3f317217, v73
	v_fma_f32 v75, v73, s9, -v75
	v_fmac_f32_e32 v75, 0x3377d1cf, v73
	v_fmac_f32_e32 v75, 0x3f317217, v73
	v_cmp_lt_f32_e64 s[0:1], |v73|, s88
	s_nop 1
	v_cndmask_b32_e64 v73, v73, v75, s[0:1]
	v_cndmask_b32_e32 v75, 0, v206, vcc
	v_sub_f32_e32 v73, v73, v75
	v_sub_f32_e32 v73, v74, v73
	ds_read_b128 v[80:83], v60 offset:896
	v_fmamk_f32 v73, v73, 0x3d800000, v72
	s_waitcnt lgkmcnt(4)
	v_mul_f32_e32 v75, v57, v97
	v_fmac_f32_e32 v75, v54, v96
	v_fmac_f32_e32 v75, v58, v98
	v_fmac_f32_e32 v75, v59, v99
	v_add_f32_e32 v78, v61, v75
	ds_read_b128 v[84:87], v60 offset:912
	s_waitcnt lgkmcnt(4)
	v_mul_f32_e32 v75, v48, v101
	v_fmac_f32_e32 v75, v25, v100
	v_fmac_f32_e32 v75, v55, v102
	v_fmac_f32_e32 v75, v56, v103
	v_add_f32_e32 v78, v78, v75
	ds_read_b128 v[88:91], v60 offset:928
	s_waitcnt lgkmcnt(4)
; #define LAS __attribute__((address_space(3)))
; __device__ __forceinline__ unsigned cvt_pk_bf16(float lo, float hi) { unsigned r; asm("v_cvt_pk_bf16_f32 %0, %1, %2" : "=v"(r) : "v"(lo), "v"(hi)); return r; }
; __device__ __forceinline__ void gla_gates(const Params& p, int l, int h, int tok0, int d, int tg, LAS float* gsum, float (&b)[16], float& blast) {
;     ...
;     const LAS float* lr = lrs + (tg * 16) * 16;
;     float run = 0.f;
; #pragma unroll
;     for (int i = 0; i < 16; ++i) {
;         float x = bg;
; #pragma unroll
;         for (int r4 = 0; r4 < 4; ++r4) { const f32x4 a = *(const LAS f32x4*)(lr + i * 16 + r4 * 4);
;             x += a[0] * w[r4 * 4] + a[1] * w[r4 * 4 + 1] + a[2] * w[r4 * 4 + 2] + a[3] * w[r4 * 4 + 3]; }
;         const float ls = fminf(x, 0.f) - __logf(1.f + __expf(-fabsf(x)));
;         run += ls * (1.f / 16.f); b[i] = run;
;     }
;     gsum[tg * 128 + d] = run;
;     __syncthreads();
;     float off = 0.f, tot = 0.f;
; #pragma unroll
;     for (int g = 0; g < 4; ++g) { const float v = gsum[g * 128 + d]; tot += v; if (g < tg) off += v; }
; #pragma unroll
;     for (int i = 0; i < 16; ++i) b[i] += off;
;     blast = tot;
; __device__ __forceinline__ void gla_local_item(const Params& p, int l, int c, int h, LAS unsigned char* lds) {
;     ...
;     {
;         unsigned* bc = (unsigned*)((u16*)(ws + WS_BCUM) + (size_t)(tok0 + tg * 16) * 512 + h * 128 + (d & ~1));
; #pragma unroll
;         for (int i = 0; i < 16; ++i) {
;             const float ev = __expf(b[i]);
;             const float eo = __shfl_down(ev, 1);
;             if ((d & 1) == 0) bc[i * 256] = cvt_pk_bf16(ev, eo);
	v_mul_f32_e32 v75, v51, v105
	v_fmac_f32_e32 v75, v50, v104
	v_fmac_f32_e32 v75, v52, v106
	v_fmac_f32_e32 v75, v53, v107
	v_add_f32_e32 v78, v78, v75
	ds_read_b128 v[92:95], v60 offset:944
	s_waitcnt lgkmcnt(4)
	v_mul_f32_e32 v75, v22, v109
	v_fmac_f32_e32 v75, v19, v108
	v_fmac_f32_e32 v75, v24, v110
	v_fmac_f32_e32 v75, v23, v111
	v_add_f32_e32 v74, v78, v75
	v_min_f32_e32 v75, 0, v74
	v_mul_f32_e64 v74, |v74|, s8
	v_exp_f32_e32 v74, v74
	s_nop 0
	v_add_f32_e32 v74, 1.0, v74
	v_cmp_gt_f32_e32 vcc, s89, v74
	s_nop 1
	v_cndmask_b32_e64 v76, 0, 32, vcc
	v_ldexp_f32 v74, v74, v76
	v_log_f32_e32 v74, v74
	s_nop 0
	v_mul_f32_e32 v76, 0x3f317217, v74
	v_fma_f32 v76, v74, s9, -v76
	v_fmac_f32_e32 v76, 0x3377d1cf, v74
	v_fmac_f32_e32 v76, 0x3f317217, v74
	v_cmp_lt_f32_e64 s[0:1], |v74|, s88
	s_nop 1
	v_cndmask_b32_e64 v74, v74, v76, s[0:1]
	v_cndmask_b32_e32 v76, 0, v206, vcc
	v_sub_f32_e32 v74, v74, v76
	ds_read_b128 v[96:99], v60 offset:960
	v_sub_f32_e32 v74, v75, v74
	v_fmamk_f32 v74, v74, 0x3d800000, v73
	s_waitcnt lgkmcnt(4)
	v_mul_f32_e32 v75, v57, v81
	v_fmac_f32_e32 v75, v54, v80
	v_fmac_f32_e32 v75, v58, v82
	v_fmac_f32_e32 v75, v59, v83
	ds_read_b128 v[100:103], v60 offset:976
	v_add_f32_e32 v75, v61, v75
	s_waitcnt lgkmcnt(4)
	v_mul_f32_e32 v77, v48, v85
	v_fmac_f32_e32 v77, v25, v84
	v_fmac_f32_e32 v77, v55, v86
	v_fmac_f32_e32 v77, v56, v87
	v_add_f32_e32 v75, v75, v77
	ds_read_b128 v[104:107], v60 offset:992
	s_waitcnt lgkmcnt(4)
	v_mul_f32_e32 v77, v51, v89
	v_fmac_f32_e32 v77, v50, v88
	v_fmac_f32_e32 v77, v52, v90
	v_fmac_f32_e32 v77, v53, v91
	v_add_f32_e32 v75, v75, v77
	ds_read_b128 v[108:111], v60 offset:1008
	s_waitcnt lgkmcnt(4)
	v_mul_f32_e32 v77, v22, v93
	v_fmac_f32_e32 v77, v19, v92
	v_fmac_f32_e32 v77, v24, v94
	v_fmac_f32_e32 v77, v23, v95
	v_add_f32_e32 v75, v75, v77
	v_min_f32_e32 v76, 0, v75
	v_mul_f32_e64 v75, |v75|, s8
	v_exp_f32_e32 v75, v75
	s_nop 0
	v_add_f32_e32 v75, 1.0, v75
	v_cmp_gt_f32_e32 vcc, s89, v75
	s_nop 1
	v_cndmask_b32_e64 v77, 0, 32, vcc
	v_ldexp_f32 v75, v75, v77
	v_log_f32_e32 v75, v75
	s_nop 0
	v_mul_f32_e32 v77, 0x3f317217, v75
	v_fma_f32 v77, v75, s9, -v77
	v_fmac_f32_e32 v77, 0x3377d1cf, v75
	v_fmac_f32_e32 v77, 0x3f317217, v75
	v_cmp_lt_f32_e64 s[0:1], |v75|, s88
	s_nop 1
	v_cndmask_b32_e64 v75, v75, v77, s[0:1]
	v_cndmask_b32_e32 v77, 0, v206, vcc
	v_sub_f32_e32 v75, v75, v77
	v_sub_f32_e32 v75, v76, v75
	v_fmamk_f32 v75, v75, 0x3d800000, v74
	s_waitcnt lgkmcnt(3)
	v_mul_f32_e32 v57, v57, v97
	v_fmac_f32_e32 v57, v54, v96
	v_fmac_f32_e32 v57, v58, v98
	v_fmac_f32_e32 v57, v59, v99
	v_add_f32_e32 v54, v61, v57
	s_waitcnt lgkmcnt(2)
	v_mul_f32_e32 v48, v48, v101
	v_fmac_f32_e32 v48, v25, v100
	v_fmac_f32_e32 v48, v55, v102
	v_fmac_f32_e32 v48, v56, v103
	v_add_f32_e32 v25, v54, v48
	s_waitcnt lgkmcnt(1)
	v_mul_f32_e32 v48, v51, v105
	v_fmac_f32_e32 v48, v50, v104
	v_fmac_f32_e32 v48, v52, v106
	v_fmac_f32_e32 v48, v53, v107
	v_add_f32_e32 v25, v25, v48
	s_waitcnt lgkmcnt(0)
	v_mul_f32_e32 v22, v22, v109
	v_fmac_f32_e32 v22, v19, v108
	v_fmac_f32_e32 v22, v24, v110
	v_fmac_f32_e32 v22, v23, v111
	v_add_f32_e32 v19, v25, v22
	v_min_f32_e32 v22, 0, v19
	v_mul_f32_e64 v19, |v19|, s8
	v_exp_f32_e32 v19, v19
	v_mov_b32_e32 v53, v1
	v_add_f32_e32 v19, 1.0, v19
	v_cmp_gt_f32_e32 vcc, s89, v19
	s_nop 1
	v_cndmask_b32_e64 v23, 0, 32, vcc
	v_ldexp_f32 v19, v19, v23
	v_log_f32_e32 v19, v19
	s_nop 0
	v_mul_f32_e32 v23, 0x3f317217, v19
	v_fma_f32 v23, v19, s9, -v23
	v_fmac_f32_e32 v23, 0x3377d1cf, v19
	v_fmac_f32_e32 v23, 0x3f317217, v19
	v_cmp_lt_f32_e64 s[0:1], |v19|, s88
	s_nop 1
	v_cndmask_b32_e64 v19, v19, v23, s[0:1]
	v_cndmask_b32_e32 v23, 0, v206, vcc
	v_sub_f32_e32 v19, v19, v23
	v_sub_f32_e32 v19, v22, v19
	v_fmamk_f32 v48, v19, 0x3d800000, v75
	v_add_u32_e32 v19, 0, v18
	v_lshl_add_u32 v22, v31, 9, v19
	ds_write_b32 v22, v48
	s_waitcnt lgkmcnt(0)
	s_barrier
	ds_read2st64_b32 v[22:23], v19 offset1:2
	v_cmp_lt_i32_e32 vcc, 0, v31
	s_waitcnt lgkmcnt(0)
	v_add_f32_e32 v22, 0, v22
	v_cndmask_b32_e32 v24, 0, v22, vcc
	v_cmp_lt_i32_e32 vcc, 1, v31
	v_add_f32_e32 v25, v23, v24
	s_nop 0
	v_cndmask_b32_e32 v50, v24, v25, vcc
	ds_read2st64_b32 v[24:25], v19 offset0:4 offset1:6
	v_cmp_lt_i32_e32 vcc, 2, v31
	s_waitcnt lgkmcnt(0)
	v_add_f32_e32 v51, v24, v50
	v_cndmask_b32_e32 v50, v50, v51, vcc
	v_cmp_lt_i32_e32 vcc, 3, v31
	v_add_f32_e32 v51, v25, v50
	s_nop 0
	v_cndmask_b32_e32 v50, v50, v51, vcc
	v_and_b32_e32 v51, 0x7e, v30
	v_lshlrev_b32_e32 v52, 1, v51
	v_add_f32_e32 v49, v49, v50
	v_lshl_add_u64 v[20:21], v[20:21], 0, v[52:53]
	v_and_b32_e32 v52, 1, v30
	v_cmp_eq_u32_e64 s[38:39], 0, v52
	v_mul_f32_e32 v52, 0x3fb8aa3b, v49
	v_and_b32_e32 v51, 63, v205
	v_exp_f32_e32 v52, v52
	v_cmp_ne_u32_e32 vcc, 63, v51
	s_nop 1
	v_addc_co_u32_e32 v51, vcc, 0, v205, vcc
	v_lshlrev_b32_e32 v51, 2, v51
	ds_bpermute_b32 v53, v51, v52
	s_and_saveexec_b64 s[0:1], s[38:39]
	s_cbranch_execz .LBB0_507
	s_waitcnt lgkmcnt(0)
	v_cvt_pk_bf16_f32 v52, v52, v53
	global_store_dword v[20:21], v52, off
